# P6 epilogue hand-written: batched sum-of-squares shuffles (2 LDS round trips instead of 16), packed squares, lane-transposed bf16 tile stores
# speedup vs baseline: 1.0043x; 1.0043x over previous
; #define PG8_STAGE(bufoff, gbase, voff) do { _Pragma("unroll") for (int _i = 0; _i < 2; ++_i) \
;         __builtin_amdgcn_global_load_lds((const unsigned*)((const char*)(gbase) + (voff)[_i]), (LAS unsigned*)(lds + (bufoff) + ldsw + _i * 8192), 16, 0, 0); } while (0)
; #define PG8_LDA(dst, b, h) do { _Pragma("unroll") for (int m = 0; m < 4; ++m) _Pragma("unroll") for (int k = 0; k < 2; ++k) dst[m][k] = *(const LAS bf16x8*)(lds + PG8_SA(b, h) + aoff + m * 2048 + k * 1024); } while (0)
; #define PG8_BAR __builtin_amdgcn_s_barrier()
; template <class Epi>
; DI void gemm_phase(LAS unsigned char* lds, const Gemm g, const StaticOrder& S_, const Epi& E) {
;     ...
;         for (int t = tb; t < te; t += 2) {
;             const bool last = (t == nt - 2);
;             const bool hA = (t >= ksplit), hB = (t + 2 >= ksplit);
;             const char* a1 = (hA ? cA1 : cA0) + (size_t)(t + 1) * kstep;
;             const char* a2 = last ? nA0 : (hB ? cA1 : cA0) + (size_t)(t + 2) * kstep; const char* b2 = last ? nB0 : (hB ? cB1 : cB0) + (size_t)(t + 2) * kstep;
;             const char* a3 = a2 + kstep; const char* b3 = b2 + kstep;
;             PG8_LDB(B0, 0, 0); PG8_SCHED; PG8_LDA(At, 0, 0); PG8_STAGE(PG8_SA(1, 1), a1 + hstepA, voffA);
;             PG8_WAIT_L(8); PG8_BAR; PG8_WAIT_L(0); PG8_MMA(0, 0, At, B0); PG8_BAR; PG8_SCHED;
;             PG8_LDB(B1, 0, 1); PG8_STAGE(PG8_SB(0, 0), b2, voffB);
;             PG8_BAR; PG8_WAIT_L(0); PG8_MMA(0, 1, At, B1); PG8_BAR;
;             PG8_LDA(At, 0, 1); PG8_STAGE(PG8_SA(0, 0), a2, voffA);
;             PG8_BAR; PG8_WAIT_L(0); PG8_MMA(1, 0, At, B0); PG8_BAR; PG8_SCHED;
;             PG8_STAGE(PG8_SB(0, 1), b2 + hstepB, voffB);
;             PG8_WAIT_V(6); PG8_BAR; PG8_MMA(1, 1, At, B1); PG8_BAR;
;             PG8_LDB(B0, 1, 0); PG8_SCHED; PG8_LDA(At, 1, 0); PG8_STAGE(PG8_SA(0, 1), a2 + hstepA, voffA);
;             PG8_WAIT_L(8); PG8_BAR; PG8_WAIT_L(0); PG8_MMA(0, 0, At, B0); PG8_BAR; PG8_SCHED;
;             PG8_LDB(B1, 1, 1); PG8_STAGE(PG8_SB(1, 0), b3, voffB);
;             PG8_BAR; PG8_WAIT_L(0); PG8_MMA(0, 1, At, B1); PG8_BAR;
;             PG8_LDA(At, 1, 1); PG8_STAGE(PG8_SA(1, 0), a3, voffA);
;             PG8_BAR; PG8_WAIT_L(0); PG8_MMA(1, 0, At, B0); PG8_BAR; PG8_SCHED;
;             PG8_STAGE(PG8_SB(1, 1), b3 + hstepB, voffB);
;             PG8_WAIT_V(6); PG8_BAR; PG8_MMA(1, 1, At, B1); PG8_BAR;
.LBB0_525:
	s_add_i32 s72, s46, 2
	s_cmp_gt_u32 s72, 29
	s_cselect_b64 s[48:49], -1, 0
	s_and_b64 vcc, s[48:49], exec
	s_cselect_b32 s48, s37, s40
	s_cselect_b32 s47, s39, s41
	s_cselect_b32 s49, s69, s43
	s_cselect_b32 s73, s68, s42
	s_add_u32 s48, s48, s44
	s_addc_u32 s47, s47, s45
	s_add_u32 s48, s48, 0xfff80080
	s_addc_u32 s47, s47, -1
	ds_read_b128 v[158:161], v153
	ds_read_b128 v[162:165], v153 offset:1024
	ds_read_b128 v[166:169], v153 offset:2048
	ds_read_b128 v[170:173], v153 offset:3072
	s_add_u32 s73, s73, s44
	s_addc_u32 s49, s49, s45
	s_add_u32 s73, s73, 0xfff80080
	s_addc_u32 s74, s49, -1
	s_cmp_eq_u32 s46, 28
	s_cselect_b32 s46, s71, s73
	s_cselect_b32 s49, s23, s47
	s_cselect_b32 s48, s70, s48
	s_cselect_b32 s47, s21, s74
	v_lshl_add_u64 v[208:209], v[146:147], 0, s[44:45]
	s_add_i32 m0, s54, 0xc000
	ds_read_b128 v[174:177], v154
	ds_read_b128 v[178:181], v154 offset:1024
	ds_read_b128 v[182:185], v154 offset:2048
	ds_read_b128 v[186:189], v154 offset:3072
	ds_read_b128 v[190:193], v154 offset:4096
	ds_read_b128 v[194:197], v154 offset:5120
	ds_read_b128 v[198:201], v154 offset:6144
	ds_read_b128 v[204:207], v154 offset:7168
	global_load_lds_dwordx4 v[208:209], off
	v_lshl_add_u64 v[208:209], v[148:149], 0, s[44:45]
	s_add_i32 m0, s54, 0xe000
	s_nop 0
	global_load_lds_dwordx4 v[208:209], off
	s_waitcnt lgkmcnt(8)
	s_setprio 1
	s_barrier
	s_waitcnt lgkmcnt(0)
	v_mfma_f32_16x16x32_bf16 v[124:127], v[158:161], v[174:177], v[124:127]
	v_mfma_f32_16x16x32_bf16 v[120:123], v[166:169], v[174:177], v[120:123]
	v_mfma_f32_16x16x32_bf16 v[108:111], v[158:161], v[182:185], v[108:111]
	v_mfma_f32_16x16x32_bf16 v[104:107], v[166:169], v[182:185], v[104:107]
	v_mfma_f32_16x16x32_bf16 v[92:95], v[158:161], v[190:193], v[92:95]
	v_mfma_f32_16x16x32_bf16 v[88:91], v[166:169], v[190:193], v[88:91]
	v_mfma_f32_16x16x32_bf16 v[76:79], v[158:161], v[198:201], v[76:79]
	v_mfma_f32_16x16x32_bf16 v[72:75], v[166:169], v[198:201], v[72:75]
	v_mfma_f32_16x16x32_bf16 v[124:127], v[162:165], v[178:181], v[124:127]
	v_mfma_f32_16x16x32_bf16 v[120:123], v[170:173], v[178:181], v[120:123]
	v_mfma_f32_16x16x32_bf16 v[108:111], v[162:165], v[186:189], v[108:111]
	v_mfma_f32_16x16x32_bf16 v[104:107], v[170:173], v[186:189], v[104:107]
	v_mfma_f32_16x16x32_bf16 v[92:95], v[162:165], v[194:197], v[92:95]
	v_mfma_f32_16x16x32_bf16 v[88:91], v[170:173], v[194:197], v[88:91]
	v_mfma_f32_16x16x32_bf16 v[76:79], v[162:165], v[204:207], v[76:79]
	v_mfma_f32_16x16x32_bf16 v[72:75], v[170:173], v[204:207], v[72:75]
	s_setprio 0
	s_barrier
	s_add_i32 s73, s66, s53
	v_lshl_add_u64 v[224:225], s[46:47], 0, v[130:131]
	s_mov_b32 m0, s73
	ds_read_b128 v[208:211], v155
	ds_read_b128 v[212:215], v155 offset:1024
	ds_read_b128 v[216:219], v155 offset:2048
	ds_read_b128 v[220:223], v155 offset:3072
	global_load_lds_dwordx4 v[224:225], off
	v_lshl_add_u64 v[226:227], s[46:47], 0, v[134:135]
	s_add_i32 m0, s73, 0x2000
	s_nop 0
	global_load_lds_dwordx4 v[226:227], off
	s_setprio 1
	s_barrier
	s_waitcnt lgkmcnt(0)
	v_mfma_f32_16x16x32_bf16 v[116:119], v[208:211], v[174:177], v[116:119]
	v_mfma_f32_16x16x32_bf16 v[112:115], v[216:219], v[174:177], v[112:115]
	v_mfma_f32_16x16x32_bf16 v[100:103], v[208:211], v[182:185], v[100:103]
	v_mfma_f32_16x16x32_bf16 v[96:99], v[216:219], v[182:185], v[96:99]
	v_mfma_f32_16x16x32_bf16 v[84:87], v[208:211], v[190:193], v[84:87]
	v_mfma_f32_16x16x32_bf16 v[80:83], v[216:219], v[190:193], v[80:83]
	v_mfma_f32_16x16x32_bf16 v[68:71], v[208:211], v[198:201], v[68:71]
	v_mfma_f32_16x16x32_bf16 v[64:67], v[216:219], v[198:201], v[64:67]
	v_mfma_f32_16x16x32_bf16 v[116:119], v[212:215], v[178:181], v[116:119]
	v_mfma_f32_16x16x32_bf16 v[112:115], v[220:223], v[178:181], v[112:115]
	v_mfma_f32_16x16x32_bf16 v[100:103], v[212:215], v[186:189], v[100:103]
	v_mfma_f32_16x16x32_bf16 v[96:99], v[220:223], v[186:189], v[96:99]
	v_mfma_f32_16x16x32_bf16 v[84:87], v[212:215], v[194:197], v[84:87]
	v_mfma_f32_16x16x32_bf16 v[80:83], v[220:223], v[194:197], v[80:83]
	v_mfma_f32_16x16x32_bf16 v[68:71], v[212:215], v[204:207], v[68:71]
	v_mfma_f32_16x16x32_bf16 v[64:67], v[220:223], v[204:207], v[64:67]
	s_setprio 0
	s_mov_b32 m0, s54
	v_lshl_add_u64 v[228:229], s[48:49], 0, v[128:129]
	s_barrier
	ds_read_b128 v[174:177], v154 offset:16384
	ds_read_b128 v[178:181], v154 offset:17408
	ds_read_b128 v[182:185], v154 offset:18432
	ds_read_b128 v[186:189], v154 offset:19456
	ds_read_b128 v[190:193], v154 offset:20480
	ds_read_b128 v[194:197], v154 offset:21504
	ds_read_b128 v[198:201], v154 offset:22528
	ds_read_b128 v[204:207], v154 offset:23552
	global_load_lds_dwordx4 v[228:229], off
	v_lshl_add_u64 v[230:231], s[48:49], 0, v[132:133]
	s_mov_b32 m0, s55
	s_nop 0
	global_load_lds_dwordx4 v[230:231], off
	s_setprio 1
	s_barrier
	s_waitcnt lgkmcnt(0)
	v_mfma_f32_16x16x32_bf16 v[60:63], v[158:161], v[174:177], v[60:63]
	v_mfma_f32_16x16x32_bf16 v[56:59], v[166:169], v[174:177], v[56:59]
	v_mfma_f32_16x16x32_bf16 v[44:47], v[158:161], v[182:185], v[44:47]
	v_mfma_f32_16x16x32_bf16 v[40:43], v[166:169], v[182:185], v[40:43]
	v_mfma_f32_16x16x32_bf16 v[28:31], v[158:161], v[190:193], v[28:31]
	v_mfma_f32_16x16x32_bf16 v[24:27], v[166:169], v[190:193], v[24:27]
	v_mfma_f32_16x16x32_bf16 v[12:15], v[158:161], v[198:201], v[12:15]
	v_mfma_f32_16x16x32_bf16 v[8:11], v[166:169], v[198:201], v[8:11]
	v_mfma_f32_16x16x32_bf16 v[60:63], v[162:165], v[178:181], v[60:63]
	v_mfma_f32_16x16x32_bf16 v[56:59], v[170:173], v[178:181], v[56:59]
	v_mfma_f32_16x16x32_bf16 v[44:47], v[162:165], v[186:189], v[44:47]
	v_mfma_f32_16x16x32_bf16 v[40:43], v[170:173], v[186:189], v[40:43]
	v_mfma_f32_16x16x32_bf16 v[28:31], v[162:165], v[194:197], v[28:31]
	v_mfma_f32_16x16x32_bf16 v[24:27], v[170:173], v[194:197], v[24:27]
	v_mfma_f32_16x16x32_bf16 v[12:15], v[162:165], v[204:207], v[12:15]
	v_mfma_f32_16x16x32_bf16 v[8:11], v[170:173], v[204:207], v[8:11]
	s_setprio 0
	s_barrier
; #define PG8_STAGE(bufoff, gbase, voff) do { _Pragma("unroll") for (int _i = 0; _i < 2; ++_i) \
;         __builtin_amdgcn_global_load_lds((const unsigned*)((const char*)(gbase) + (voff)[_i]), (LAS unsigned*)(lds + (bufoff) + ldsw + _i * 8192), 16, 0, 0); } while (0)
; #define PG8_LDA(dst, b, h) do { _Pragma("unroll") for (int m = 0; m < 4; ++m) _Pragma("unroll") for (int k = 0; k < 2; ++k) dst[m][k] = *(const LAS bf16x8*)(lds + PG8_SA(b, h) + aoff + m * 2048 + k * 1024); } while (0)
; #define PG8_LDB(dst, b, h) do { _Pragma("unroll") for (int n = 0; n < 2; ++n) _Pragma("unroll") for (int k = 0; k < 2; ++k) dst[n][k] = *(const LAS bf16x8*)(lds + PG8_SB(b, h) + boff + n * 2048 + k * 1024); } while (0)
; #define PG8_MMA(ai, bj, At, Bt) do { __builtin_amdgcn_s_setprio(1); _Pragma("unroll") for (int m = 0; m < 4; ++m) _Pragma("unroll") for (int n = 0; n < 2; ++n) _Pragma("unroll") for (int k = 0; k < 2; ++k) \
;         acc[ai][bj][m][n] = __builtin_amdgcn_mfma_f32_16x16x32_bf16(Bt[n][k], At[m][k], acc[ai][bj][m][n], 0, 0, 0); __builtin_amdgcn_s_setprio(0); } while (0)
; #define PG8_WAIT_V(n) asm volatile("s_waitcnt vmcnt(" #n ")" ::: "memory")
; #define PG8_WAIT_L(n) asm volatile("s_waitcnt lgkmcnt(" #n ")" ::: "memory")
; #define PG8_BAR __builtin_amdgcn_s_barrier()
; #define PG8_SCHED __builtin_amdgcn_sched_barrier(0)
; template <class Epi>
; DI void gemm_phase(LAS unsigned char* lds, const Gemm g, const StaticOrder& S_, const Epi& E) {
;     ...
;             PG8_WAIT_V(6); PG8_BAR; PG8_MMA(1, 1, At, B1); PG8_BAR;
;             PG8_LDB(B0, 1, 0); PG8_SCHED; PG8_LDA(At, 1, 0); PG8_STAGE(PG8_SA(0, 1), a2 + hstepA, voffA);
;             PG8_WAIT_L(8); PG8_BAR; PG8_WAIT_L(0); PG8_MMA(0, 0, At, B0); PG8_BAR; PG8_SCHED;
;             PG8_LDB(B1, 1, 1); PG8_STAGE(PG8_SB(1, 0), b3, voffB);
;             PG8_BAR; PG8_WAIT_L(0); PG8_MMA(0, 1, At, B1); PG8_BAR;
;             PG8_LDA(At, 1, 1); PG8_STAGE(PG8_SA(1, 0), a3, voffA);
;             PG8_BAR; PG8_WAIT_L(0); PG8_MMA(1, 0, At, B0); PG8_BAR; PG8_SCHED;
;             PG8_STAGE(PG8_SB(1, 1), b3 + hstepB, voffB);
;             PG8_WAIT_V(6); PG8_BAR; PG8_MMA(1, 1, At, B1); PG8_BAR;
	s_add_u32 s74, s46, 0x80000
	s_addc_u32 s75, s47, 0
	s_add_i32 s73, s67, s53
	v_lshl_add_u64 v[158:159], s[74:75], 0, v[130:131]
	s_mov_b32 m0, s73
	s_nop 0
	global_load_lds_dwordx4 v[158:159], off
	v_lshl_add_u64 v[158:159], s[74:75], 0, v[134:135]
	s_add_i32 m0, s73, 0x2000
	s_nop 0
	global_load_lds_dwordx4 v[158:159], off
	s_waitcnt vmcnt(6)
	s_setprio 1
	s_barrier
	v_mfma_f32_16x16x32_bf16 v[52:55], v[208:211], v[174:177], v[52:55]
	v_mfma_f32_16x16x32_bf16 v[48:51], v[216:219], v[174:177], v[48:51]
	v_mfma_f32_16x16x32_bf16 v[36:39], v[208:211], v[182:185], v[36:39]
	v_mfma_f32_16x16x32_bf16 v[32:35], v[216:219], v[182:185], v[32:35]
	v_mfma_f32_16x16x32_bf16 v[20:23], v[208:211], v[190:193], v[20:23]
	v_mfma_f32_16x16x32_bf16 v[16:19], v[216:219], v[190:193], v[16:19]
	v_mfma_f32_16x16x32_bf16 v[4:7], v[208:211], v[198:201], v[4:7]
	v_mfma_f32_16x16x32_bf16 v[0:3], v[216:219], v[198:201], v[0:3]
	v_mfma_f32_16x16x32_bf16 v[52:55], v[212:215], v[178:181], v[52:55]
	v_mfma_f32_16x16x32_bf16 v[48:51], v[220:223], v[178:181], v[48:51]
	v_mfma_f32_16x16x32_bf16 v[36:39], v[212:215], v[186:189], v[36:39]
	v_mfma_f32_16x16x32_bf16 v[32:35], v[220:223], v[186:189], v[32:35]
	v_mfma_f32_16x16x32_bf16 v[20:23], v[212:215], v[194:197], v[20:23]
	v_mfma_f32_16x16x32_bf16 v[16:19], v[220:223], v[194:197], v[16:19]
	v_mfma_f32_16x16x32_bf16 v[4:7], v[212:215], v[204:207], v[4:7]
	v_mfma_f32_16x16x32_bf16 v[0:3], v[220:223], v[204:207], v[0:3]
	s_setprio 0
	s_add_i32 s73, 0, 0x18000
	v_add_u32_e32 v136, s73, v151
	s_barrier
	ds_read_b128 v[158:161], v136
	ds_read_b128 v[162:165], v136 offset:1024
	ds_read_b128 v[166:169], v136 offset:2048
	ds_read_b128 v[170:173], v136 offset:3072
	s_add_u32 s48, s48, 0x80000
	s_addc_u32 s49, s49, 0
	s_mov_b32 m0, s56
	v_lshl_add_u64 v[208:209], s[48:49], 0, v[128:129]
	ds_read_b128 v[174:177], v154 offset:32768
	ds_read_b128 v[178:181], v154 offset:33792
	ds_read_b128 v[182:185], v154 offset:34816
	ds_read_b128 v[186:189], v154 offset:35840
	ds_read_b128 v[190:193], v154 offset:36864
	ds_read_b128 v[194:197], v154 offset:37888
	ds_read_b128 v[198:201], v154 offset:38912
	ds_read_b128 v[204:207], v154 offset:39936
	global_load_lds_dwordx4 v[208:209], off
	v_lshl_add_u64 v[208:209], s[48:49], 0, v[132:133]
	s_mov_b32 m0, s57
	s_nop 0
	global_load_lds_dwordx4 v[208:209], off
	s_waitcnt lgkmcnt(8)
	s_setprio 1
	s_barrier
	s_waitcnt lgkmcnt(0)
	v_mfma_f32_16x16x32_bf16 v[124:127], v[158:161], v[174:177], v[124:127]
	v_mfma_f32_16x16x32_bf16 v[120:123], v[166:169], v[174:177], v[120:123]
	v_mfma_f32_16x16x32_bf16 v[108:111], v[158:161], v[182:185], v[108:111]
	v_mfma_f32_16x16x32_bf16 v[104:107], v[166:169], v[182:185], v[104:107]
	v_mfma_f32_16x16x32_bf16 v[92:95], v[158:161], v[190:193], v[92:95]
	v_mfma_f32_16x16x32_bf16 v[88:91], v[166:169], v[190:193], v[88:91]
	v_mfma_f32_16x16x32_bf16 v[76:79], v[158:161], v[198:201], v[76:79]
	v_mfma_f32_16x16x32_bf16 v[72:75], v[166:169], v[198:201], v[72:75]
	v_mfma_f32_16x16x32_bf16 v[124:127], v[162:165], v[178:181], v[124:127]
	v_mfma_f32_16x16x32_bf16 v[120:123], v[170:173], v[178:181], v[120:123]
	v_mfma_f32_16x16x32_bf16 v[108:111], v[162:165], v[186:189], v[108:111]
	v_mfma_f32_16x16x32_bf16 v[104:107], v[170:173], v[186:189], v[104:107]
	v_mfma_f32_16x16x32_bf16 v[92:95], v[162:165], v[194:197], v[92:95]
	v_mfma_f32_16x16x32_bf16 v[88:91], v[170:173], v[194:197], v[88:91]
	v_mfma_f32_16x16x32_bf16 v[76:79], v[162:165], v[204:207], v[76:79]
	v_mfma_f32_16x16x32_bf16 v[72:75], v[170:173], v[204:207], v[72:75]
	s_setprio 0
	s_barrier
	s_add_i32 s48, 0, 0x1c000
	s_add_i32 s49, s73, s53
	v_add_u32_e32 v136, s48, v151
	v_lshl_add_u64 v[224:225], v[224:225], 0, s[16:17]
	s_mov_b32 m0, s49
	ds_read_b128 v[208:211], v136
	ds_read_b128 v[212:215], v136 offset:1024
	ds_read_b128 v[216:219], v136 offset:2048
	ds_read_b128 v[220:223], v136 offset:3072
	global_load_lds_dwordx4 v[224:225], off
	v_lshl_add_u64 v[224:225], v[226:227], 0, s[16:17]
	s_add_i32 m0, s49, 0x2000
	s_nop 0
	global_load_lds_dwordx4 v[224:225], off
	s_setprio 1
	s_barrier
	s_waitcnt lgkmcnt(0)
	v_mfma_f32_16x16x32_bf16 v[116:119], v[208:211], v[174:177], v[116:119]
	v_mfma_f32_16x16x32_bf16 v[112:115], v[216:219], v[174:177], v[112:115]
	v_mfma_f32_16x16x32_bf16 v[100:103], v[208:211], v[182:185], v[100:103]
	v_mfma_f32_16x16x32_bf16 v[96:99], v[216:219], v[182:185], v[96:99]
	v_mfma_f32_16x16x32_bf16 v[84:87], v[208:211], v[190:193], v[84:87]
	v_mfma_f32_16x16x32_bf16 v[80:83], v[216:219], v[190:193], v[80:83]
	v_mfma_f32_16x16x32_bf16 v[68:71], v[208:211], v[198:201], v[68:71]
	v_mfma_f32_16x16x32_bf16 v[64:67], v[216:219], v[198:201], v[64:67]
	v_mfma_f32_16x16x32_bf16 v[116:119], v[212:215], v[178:181], v[116:119]
	v_mfma_f32_16x16x32_bf16 v[112:115], v[220:223], v[178:181], v[112:115]
	v_mfma_f32_16x16x32_bf16 v[100:103], v[212:215], v[186:189], v[100:103]
	v_mfma_f32_16x16x32_bf16 v[96:99], v[220:223], v[186:189], v[96:99]
	v_mfma_f32_16x16x32_bf16 v[84:87], v[212:215], v[194:197], v[84:87]
	v_mfma_f32_16x16x32_bf16 v[80:83], v[220:223], v[194:197], v[80:83]
	v_mfma_f32_16x16x32_bf16 v[68:71], v[212:215], v[204:207], v[68:71]
	v_mfma_f32_16x16x32_bf16 v[64:67], v[220:223], v[204:207], v[64:67]
	s_setprio 0
	s_mov_b32 m0, s59
	v_lshl_add_u64 v[224:225], v[228:229], 0, s[16:17]
	s_barrier
	ds_read_b128 v[174:177], v154 offset:49152
	ds_read_b128 v[178:181], v154 offset:50176
	ds_read_b128 v[182:185], v154 offset:51200
	ds_read_b128 v[186:189], v154 offset:52224
	ds_read_b128 v[190:193], v154 offset:53248
	ds_read_b128 v[194:197], v154 offset:54272
	ds_read_b128 v[198:201], v154 offset:55296
	ds_read_b128 v[204:207], v154 offset:56320
	global_load_lds_dwordx4 v[224:225], off
	v_lshl_add_u64 v[224:225], v[230:231], 0, s[16:17]
	s_mov_b32 m0, s60
	s_nop 0
	global_load_lds_dwordx4 v[224:225], off
	s_setprio 1
	s_barrier
; DI unsigned cvtpk(float lo, float hi) { unsigned r; asm volatile("v_cvt_pk_bf16_f32 %0, %1, %2" : "=v"(r) : "v"(lo), "v"(hi)); return r; }
; #define PG8_STAGE(bufoff, gbase, voff) do { _Pragma("unroll") for (int _i = 0; _i < 2; ++_i) \
;         __builtin_amdgcn_global_load_lds((const unsigned*)((const char*)(gbase) + (voff)[_i]), (LAS unsigned*)(lds + (bufoff) + ldsw + _i * 8192), 16, 0, 0); } while (0)
; #define PG8_LDA(dst, b, h) do { _Pragma("unroll") for (int m = 0; m < 4; ++m) _Pragma("unroll") for (int k = 0; k < 2; ++k) dst[m][k] = *(const LAS bf16x8*)(lds + PG8_SA(b, h) + aoff + m * 2048 + k * 1024); } while (0)
; #define PG8_WAIT_V(n) asm volatile("s_waitcnt vmcnt(" #n ")" ::: "memory")
; template <class Epi>
; DI void gemm_phase(LAS unsigned char* lds, const Gemm g, const StaticOrder& S_, const Epi& E) {
;     ...
;             PG8_BAR; PG8_WAIT_L(0); PG8_MMA(0, 1, At, B1); PG8_BAR;
;             PG8_LDA(At, 1, 1); PG8_STAGE(PG8_SA(1, 0), a3, voffA);
;             PG8_BAR; PG8_WAIT_L(0); PG8_MMA(1, 0, At, B0); PG8_BAR; PG8_SCHED;
;             PG8_STAGE(PG8_SB(1, 1), b3 + hstepB, voffB);
;             PG8_WAIT_V(6); PG8_BAR; PG8_MMA(1, 1, At, B1); PG8_BAR;
;     DI void operator()(const f32x4 (&acc)[2][2][4][2], const pg8::Unit& u, int wr, int wc, int fr, int fq) const {
;         unsigned char* o2 = ws + WS_OUT2; float* ssq = (float*)(ws + WS_SSQ);
;         const unsigned r0_ = (unsigned)(u.pm * 256 + wr * 64 + fr), c0_ = (unsigned)(u.pn * 256 + wc * 32 + 8 * fq) * 2u;
; #pragma unroll
;         for (int ai = 0; ai < 2; ++ai)
; #pragma unroll
;             for (int m = 0; m < 4; ++m) {
;                 const unsigned row = r0_ + ai * 128 + m * 16; float s = 0.f;
; #pragma unroll
;                 for (int bj = 0; bj < 2; ++bj) {
;                     const f32x4 v0 = acc[ai][bj][m][0], v1 = acc[ai][bj][m][1];
;                     s += v0[0] * v0[0] + v0[1] * v0[1] + v0[2] * v0[2] + v0[3] * v0[3] + v1[0] * v1[0] + v1[1] * v1[1] + v1[2] * v1[2] + v1[3] * v1[3];
;                     u32x4 w = {cvtpk(v0[0], v0[1]), cvtpk(v0[2], v0[3]), cvtpk(v1[0], v1[1]), cvtpk(v1[2], v1[3])};
;                     stg128(o2, row * 4096u + c0_ + bj * 256u, w);
;                 }
;                 s += __shfl_xor(s, 16); s += __shfl_xor(s, 32);
;                 if (fq == 0) ssq[(size_t)row * 32 + u.pn * 4 + wc] = s;
;             }
	s_waitcnt lgkmcnt(0)
	v_mfma_f32_16x16x32_bf16 v[60:63], v[158:161], v[174:177], v[60:63]
	v_mfma_f32_16x16x32_bf16 v[56:59], v[166:169], v[174:177], v[56:59]
	v_mfma_f32_16x16x32_bf16 v[44:47], v[158:161], v[182:185], v[44:47]
	v_mfma_f32_16x16x32_bf16 v[40:43], v[166:169], v[182:185], v[40:43]
	v_mfma_f32_16x16x32_bf16 v[28:31], v[158:161], v[190:193], v[28:31]
	v_mfma_f32_16x16x32_bf16 v[24:27], v[166:169], v[190:193], v[24:27]
	v_mfma_f32_16x16x32_bf16 v[12:15], v[158:161], v[198:201], v[12:15]
	v_mfma_f32_16x16x32_bf16 v[8:11], v[166:169], v[198:201], v[8:11]
	v_mfma_f32_16x16x32_bf16 v[60:63], v[162:165], v[178:181], v[60:63]
	v_mfma_f32_16x16x32_bf16 v[56:59], v[170:173], v[178:181], v[56:59]
	v_mfma_f32_16x16x32_bf16 v[44:47], v[162:165], v[186:189], v[44:47]
	v_mfma_f32_16x16x32_bf16 v[40:43], v[170:173], v[186:189], v[40:43]
	v_mfma_f32_16x16x32_bf16 v[28:31], v[162:165], v[194:197], v[28:31]
	v_mfma_f32_16x16x32_bf16 v[24:27], v[170:173], v[194:197], v[24:27]
	v_mfma_f32_16x16x32_bf16 v[12:15], v[162:165], v[204:207], v[12:15]
	v_mfma_f32_16x16x32_bf16 v[8:11], v[170:173], v[204:207], v[8:11]
	s_setprio 0
	s_barrier
	s_add_u32 s46, s46, 0x80080
	s_addc_u32 s47, s47, 0
	s_add_i32 s48, s48, s53
	v_lshl_add_u64 v[158:159], s[46:47], 0, v[130:131]
	s_mov_b32 m0, s48
	s_nop 0
	global_load_lds_dwordx4 v[158:159], off
	v_lshl_add_u64 v[158:159], s[46:47], 0, v[134:135]
	s_add_i32 m0, s48, 0x2000
	s_nop 0
	global_load_lds_dwordx4 v[158:159], off
	s_waitcnt vmcnt(6)
	s_setprio 1
	s_barrier
	v_mfma_f32_16x16x32_bf16 v[52:55], v[208:211], v[174:177], v[52:55]
	v_mfma_f32_16x16x32_bf16 v[48:51], v[216:219], v[174:177], v[48:51]
	v_mfma_f32_16x16x32_bf16 v[36:39], v[208:211], v[182:185], v[36:39]
	v_mfma_f32_16x16x32_bf16 v[32:35], v[216:219], v[182:185], v[32:35]
	v_mfma_f32_16x16x32_bf16 v[20:23], v[208:211], v[190:193], v[20:23]
	v_mfma_f32_16x16x32_bf16 v[16:19], v[216:219], v[190:193], v[16:19]
	v_mfma_f32_16x16x32_bf16 v[4:7], v[208:211], v[198:201], v[4:7]
	v_mfma_f32_16x16x32_bf16 v[0:3], v[216:219], v[198:201], v[0:3]
	v_mfma_f32_16x16x32_bf16 v[52:55], v[212:215], v[178:181], v[52:55]
	v_mfma_f32_16x16x32_bf16 v[48:51], v[220:223], v[178:181], v[48:51]
	v_mfma_f32_16x16x32_bf16 v[36:39], v[212:215], v[186:189], v[36:39]
	v_mfma_f32_16x16x32_bf16 v[32:35], v[220:223], v[186:189], v[32:35]
	v_mfma_f32_16x16x32_bf16 v[20:23], v[212:215], v[194:197], v[20:23]
	v_mfma_f32_16x16x32_bf16 v[16:19], v[220:223], v[194:197], v[16:19]
	v_mfma_f32_16x16x32_bf16 v[4:7], v[212:215], v[204:207], v[4:7]
	v_mfma_f32_16x16x32_bf16 v[0:3], v[220:223], v[204:207], v[0:3]
	s_setprio 0
	s_add_u32 s44, s44, 0x100
	s_addc_u32 s45, s45, 0
	s_mov_b32 s46, s72
	s_barrier
	s_cbranch_vccz .LBB0_525
	v_lshl_add_u32 v136, s38, 8, v150
	v_lshrrev_b32_e32 v146, 1, v152
	v_lshl_add_u32 v146, s36, 8, v146
	s_movk_i32 s40, 0x800
	s_lshl_b32 s36, s36, 2
	s_ashr_i32 s37, s36, 31
	s_lshl_b64 s[36:37], s[36:37], 2
	s_add_u32 s36, s61, s36
	s_addc_u32 s37, s62, s37
	v_and_b32_e32 v190, 63, v202
	v_xor_b32_e32 v191, 32, v190
	v_xor_b32_e32 v190, 16, v190
	v_lshlrev_b32_e32 v190, 2, v190
	v_lshlrev_b32_e32 v191, 2, v191
	v_lshlrev_b32_e32 v200, 7, v136
	v_pk_mul_f32 v[184:185], v[112:113], v[112:113]
	v_pk_fma_f32 v[184:185], v[114:115], v[114:115], v[184:185]
	v_pk_fma_f32 v[184:185], v[116:117], v[116:117], v[184:185]
	v_pk_fma_f32 v[184:185], v[118:119], v[118:119], v[184:185]
	v_pk_fma_f32 v[184:185], v[120:121], v[120:121], v[184:185]
	v_pk_fma_f32 v[184:185], v[122:123], v[122:123], v[184:185]
	v_pk_fma_f32 v[184:185], v[124:125], v[124:125], v[184:185]
	v_pk_fma_f32 v[184:185], v[126:127], v[126:127], v[184:185]
	v_add_f32_e32 v176, v184, v185
	v_pk_mul_f32 v[186:187], v[96:97], v[96:97]
	v_pk_fma_f32 v[186:187], v[98:99], v[98:99], v[186:187]
	v_pk_fma_f32 v[186:187], v[100:101], v[100:101], v[186:187]
	v_pk_fma_f32 v[186:187], v[102:103], v[102:103], v[186:187]
	v_pk_fma_f32 v[186:187], v[104:105], v[104:105], v[186:187]
	v_pk_fma_f32 v[186:187], v[106:107], v[106:107], v[186:187]
	v_pk_fma_f32 v[186:187], v[108:109], v[108:109], v[186:187]
	v_pk_fma_f32 v[186:187], v[110:111], v[110:111], v[186:187]
	v_add_f32_e32 v177, v186, v187
	v_pk_mul_f32 v[184:185], v[80:81], v[80:81]
	v_pk_fma_f32 v[184:185], v[82:83], v[82:83], v[184:185]
	v_pk_fma_f32 v[184:185], v[84:85], v[84:85], v[184:185]
	v_pk_fma_f32 v[184:185], v[86:87], v[86:87], v[184:185]
	v_pk_fma_f32 v[184:185], v[88:89], v[88:89], v[184:185]
	v_pk_fma_f32 v[184:185], v[90:91], v[90:91], v[184:185]
	v_pk_fma_f32 v[184:185], v[92:93], v[92:93], v[184:185]
	v_pk_fma_f32 v[184:185], v[94:95], v[94:95], v[184:185]
	v_add_f32_e32 v178, v184, v185
	v_pk_mul_f32 v[186:187], v[64:65], v[64:65]
	v_pk_fma_f32 v[186:187], v[66:67], v[66:67], v[186:187]
	v_pk_fma_f32 v[186:187], v[68:69], v[68:69], v[186:187]
	v_pk_fma_f32 v[186:187], v[70:71], v[70:71], v[186:187]
	v_pk_fma_f32 v[186:187], v[72:73], v[72:73], v[186:187]
	v_pk_fma_f32 v[186:187], v[74:75], v[74:75], v[186:187]
	v_pk_fma_f32 v[186:187], v[76:77], v[76:77], v[186:187]
	v_pk_fma_f32 v[186:187], v[78:79], v[78:79], v[186:187]
	v_add_f32_e32 v179, v186, v187
	v_pk_mul_f32 v[184:185], v[48:49], v[48:49]
	v_pk_fma_f32 v[184:185], v[50:51], v[50:51], v[184:185]
	v_pk_fma_f32 v[184:185], v[52:53], v[52:53], v[184:185]
	v_pk_fma_f32 v[184:185], v[54:55], v[54:55], v[184:185]
	v_pk_fma_f32 v[184:185], v[56:57], v[56:57], v[184:185]
	v_pk_fma_f32 v[184:185], v[58:59], v[58:59], v[184:185]
	v_pk_fma_f32 v[184:185], v[60:61], v[60:61], v[184:185]
	v_pk_fma_f32 v[184:185], v[62:63], v[62:63], v[184:185]
	v_add_f32_e32 v180, v184, v185
	v_pk_mul_f32 v[186:187], v[32:33], v[32:33]
; DI unsigned cvtpk(float lo, float hi) { unsigned r; asm volatile("v_cvt_pk_bf16_f32 %0, %1, %2" : "=v"(r) : "v"(lo), "v"(hi)); return r; }
;     DI void operator()(const f32x4 (&acc)[2][2][4][2], const pg8::Unit& u, int wr, int wc, int fr, int fq) const {
;         unsigned char* o2 = ws + WS_OUT2; float* ssq = (float*)(ws + WS_SSQ);
;         const unsigned r0_ = (unsigned)(u.pm * 256 + wr * 64 + fr), c0_ = (unsigned)(u.pn * 256 + wc * 32 + 8 * fq) * 2u;
; #pragma unroll
;         for (int ai = 0; ai < 2; ++ai)
; #pragma unroll
;             for (int m = 0; m < 4; ++m) {
;                 const unsigned row = r0_ + ai * 128 + m * 16; float s = 0.f;
; #pragma unroll
;                 for (int bj = 0; bj < 2; ++bj) {
;                     const f32x4 v0 = acc[ai][bj][m][0], v1 = acc[ai][bj][m][1];
;                     s += v0[0] * v0[0] + v0[1] * v0[1] + v0[2] * v0[2] + v0[3] * v0[3] + v1[0] * v1[0] + v1[1] * v1[1] + v1[2] * v1[2] + v1[3] * v1[3];
;                     u32x4 w = {cvtpk(v0[0], v0[1]), cvtpk(v0[2], v0[3]), cvtpk(v1[0], v1[1]), cvtpk(v1[2], v1[3])};
;                     stg128(o2, row * 4096u + c0_ + bj * 256u, w);
;                 }
;                 s += __shfl_xor(s, 16); s += __shfl_xor(s, 32);
;                 if (fq == 0) ssq[(size_t)row * 32 + u.pn * 4 + wc] = s;
;             }
	v_pk_fma_f32 v[186:187], v[34:35], v[34:35], v[186:187]
	v_pk_fma_f32 v[186:187], v[36:37], v[36:37], v[186:187]
	v_pk_fma_f32 v[186:187], v[38:39], v[38:39], v[186:187]
	v_pk_fma_f32 v[186:187], v[40:41], v[40:41], v[186:187]
	v_pk_fma_f32 v[186:187], v[42:43], v[42:43], v[186:187]
	v_pk_fma_f32 v[186:187], v[44:45], v[44:45], v[186:187]
	v_pk_fma_f32 v[186:187], v[46:47], v[46:47], v[186:187]
	v_add_f32_e32 v181, v186, v187
	v_pk_mul_f32 v[184:185], v[16:17], v[16:17]
	v_pk_fma_f32 v[184:185], v[18:19], v[18:19], v[184:185]
	v_pk_fma_f32 v[184:185], v[20:21], v[20:21], v[184:185]
	v_pk_fma_f32 v[184:185], v[22:23], v[22:23], v[184:185]
	v_pk_fma_f32 v[184:185], v[24:25], v[24:25], v[184:185]
	v_pk_fma_f32 v[184:185], v[26:27], v[26:27], v[184:185]
	v_pk_fma_f32 v[184:185], v[28:29], v[28:29], v[184:185]
	v_pk_fma_f32 v[184:185], v[30:31], v[30:31], v[184:185]
	v_add_f32_e32 v182, v184, v185
	v_pk_mul_f32 v[186:187], v[0:1], v[0:1]
	v_pk_fma_f32 v[186:187], v[2:3], v[2:3], v[186:187]
	v_pk_fma_f32 v[186:187], v[4:5], v[4:5], v[186:187]
	v_pk_fma_f32 v[186:187], v[6:7], v[6:7], v[186:187]
	v_pk_fma_f32 v[186:187], v[8:9], v[8:9], v[186:187]
	v_pk_fma_f32 v[186:187], v[10:11], v[10:11], v[186:187]
	v_pk_fma_f32 v[186:187], v[12:13], v[12:13], v[186:187]
	v_pk_fma_f32 v[186:187], v[14:15], v[14:15], v[186:187]
	v_add_f32_e32 v183, v186, v187
	ds_bpermute_b32 v192, v190, v176
	ds_bpermute_b32 v193, v190, v177
	ds_bpermute_b32 v194, v190, v178
	ds_bpermute_b32 v195, v190, v179
	ds_bpermute_b32 v196, v190, v180
	ds_bpermute_b32 v197, v190, v181
	ds_bpermute_b32 v198, v190, v182
	ds_bpermute_b32 v199, v190, v183
	s_waitcnt lgkmcnt(7)
	v_add_f32_e32 v176, v176, v192
	s_waitcnt lgkmcnt(6)
	v_add_f32_e32 v177, v177, v193
	s_waitcnt lgkmcnt(5)
	v_add_f32_e32 v178, v178, v194
	s_waitcnt lgkmcnt(4)
	v_add_f32_e32 v179, v179, v195
	s_waitcnt lgkmcnt(3)
	v_add_f32_e32 v180, v180, v196
	s_waitcnt lgkmcnt(2)
	v_add_f32_e32 v181, v181, v197
	s_waitcnt lgkmcnt(1)
	v_add_f32_e32 v182, v182, v198
	s_waitcnt lgkmcnt(0)
	v_add_f32_e32 v183, v183, v199
	ds_bpermute_b32 v192, v191, v176
	ds_bpermute_b32 v193, v191, v177
	ds_bpermute_b32 v194, v191, v178
	ds_bpermute_b32 v195, v191, v179
	ds_bpermute_b32 v196, v191, v180
	ds_bpermute_b32 v197, v191, v181
	ds_bpermute_b32 v198, v191, v182
	ds_bpermute_b32 v199, v191, v183
	s_waitcnt lgkmcnt(7)
	v_add_f32_e32 v176, v176, v192
	s_waitcnt lgkmcnt(6)
	v_add_f32_e32 v177, v177, v193
	s_waitcnt lgkmcnt(5)
	v_add_f32_e32 v178, v178, v194
	s_waitcnt lgkmcnt(4)
	v_add_f32_e32 v179, v179, v195
	s_waitcnt lgkmcnt(3)
	v_add_f32_e32 v180, v180, v196
	s_waitcnt lgkmcnt(2)
	v_add_f32_e32 v181, v181, v197
	s_waitcnt lgkmcnt(1)
	v_add_f32_e32 v182, v182, v198
	s_waitcnt lgkmcnt(0)
	v_add_f32_e32 v183, v183, v199
	v_and_b32_e32 v213, 15, v202
	v_bfe_u32 v214, v202, 2, 4
	v_bfe_u32 v215, v202, 4, 2
	v_and_b32_e32 v216, 3, v202
	v_sub_u32_e32 v217, v214, v213
	v_add_u32_e32 v217, v136, v217
	v_sub_u32_e32 v218, v216, v215
	v_lshl_add_u32 v234, v218, 3, v146
	v_mov_b32_e32 v235, 0
	v_lshl_or_b32 v220, v216, 4, v214
	v_lshlrev_b32_e32 v220, 2, v220
	v_lshl_add_u64 v[236:237], v[234:235], 1, s[18:19]
	v_mov_b32_e32 v239, 0
	v_mul_lo_u32 v238, v217, s40
	v_lshl_add_u64 v[224:225], v[238:239], 1, v[236:237]
	v_cvt_pk_bf16_f32 v160, v124, v125
	v_cvt_pk_bf16_f32 v161, v126, v127
	v_cvt_pk_bf16_f32 v162, v120, v121
	v_cvt_pk_bf16_f32 v163, v122, v123
	ds_bpermute_b32 v124, v220, v160
	ds_bpermute_b32 v125, v220, v161
	ds_bpermute_b32 v126, v220, v162
	ds_bpermute_b32 v127, v220, v163
	v_cvt_pk_bf16_f32 v164, v116, v117
	v_cvt_pk_bf16_f32 v165, v118, v119
	v_cvt_pk_bf16_f32 v166, v112, v113
	v_cvt_pk_bf16_f32 v167, v114, v115
	ds_bpermute_b32 v116, v220, v164
	ds_bpermute_b32 v117, v220, v165
	ds_bpermute_b32 v118, v220, v166
	ds_bpermute_b32 v119, v220, v167
	s_waitcnt lgkmcnt(4)
	global_store_dwordx4 v[224:225], v[124:127], off
	v_add_u32_e32 v238, 16, v217
	v_mul_lo_u32 v238, v238, s40
	v_lshl_add_u64 v[226:227], v[238:239], 1, v[236:237]
	v_cvt_pk_bf16_f32 v168, v108, v109
	v_cvt_pk_bf16_f32 v169, v110, v111
	v_cvt_pk_bf16_f32 v170, v104, v105
	v_cvt_pk_bf16_f32 v171, v106, v107
	ds_bpermute_b32 v108, v220, v168
	ds_bpermute_b32 v109, v220, v169
	ds_bpermute_b32 v110, v220, v170
	ds_bpermute_b32 v111, v220, v171
	s_waitcnt lgkmcnt(4)
	global_store_dwordx4 v[224:225], v[116:119], off offset:256
	v_cvt_pk_bf16_f32 v172, v100, v101
	v_cvt_pk_bf16_f32 v173, v102, v103
	v_cvt_pk_bf16_f32 v174, v96, v97
	v_cvt_pk_bf16_f32 v175, v98, v99
	ds_bpermute_b32 v100, v220, v172
	ds_bpermute_b32 v101, v220, v173
	ds_bpermute_b32 v102, v220, v174
	ds_bpermute_b32 v103, v220, v175
	s_waitcnt lgkmcnt(4)
	global_store_dwordx4 v[226:227], v[108:111], off
	v_add_u32_e32 v238, 32, v217
	v_mul_lo_u32 v238, v238, s40
	v_lshl_add_u64 v[228:229], v[238:239], 1, v[236:237]
	v_cvt_pk_bf16_f32 v160, v92, v93
	v_cvt_pk_bf16_f32 v161, v94, v95
	v_cvt_pk_bf16_f32 v162, v88, v89
	v_cvt_pk_bf16_f32 v163, v90, v91
	ds_bpermute_b32 v92, v220, v160
	ds_bpermute_b32 v93, v220, v161
	ds_bpermute_b32 v94, v220, v162
	ds_bpermute_b32 v95, v220, v163
	s_waitcnt lgkmcnt(4)
; DI unsigned cvtpk(float lo, float hi) { unsigned r; asm volatile("v_cvt_pk_bf16_f32 %0, %1, %2" : "=v"(r) : "v"(lo), "v"(hi)); return r; }
;     DI void operator()(const f32x4 (&acc)[2][2][4][2], const pg8::Unit& u, int wr, int wc, int fr, int fq) const {
;         unsigned char* o2 = ws + WS_OUT2; float* ssq = (float*)(ws + WS_SSQ);
;         const unsigned r0_ = (unsigned)(u.pm * 256 + wr * 64 + fr), c0_ = (unsigned)(u.pn * 256 + wc * 32 + 8 * fq) * 2u;
; #pragma unroll
;         for (int ai = 0; ai < 2; ++ai)
; #pragma unroll
;             for (int m = 0; m < 4; ++m) {
;                 const unsigned row = r0_ + ai * 128 + m * 16; float s = 0.f;
; #pragma unroll
;                 for (int bj = 0; bj < 2; ++bj) {
;                     const f32x4 v0 = acc[ai][bj][m][0], v1 = acc[ai][bj][m][1];
;                     s += v0[0] * v0[0] + v0[1] * v0[1] + v0[2] * v0[2] + v0[3] * v0[3] + v1[0] * v1[0] + v1[1] * v1[1] + v1[2] * v1[2] + v1[3] * v1[3];
;                     u32x4 w = {cvtpk(v0[0], v0[1]), cvtpk(v0[2], v0[3]), cvtpk(v1[0], v1[1]), cvtpk(v1[2], v1[3])};
;                     stg128(o2, row * 4096u + c0_ + bj * 256u, w);
;                 }
;                 s += __shfl_xor(s, 16); s += __shfl_xor(s, 32);
;                 if (fq == 0) ssq[(size_t)row * 32 + u.pn * 4 + wc] = s;
;             }
	global_store_dwordx4 v[226:227], v[100:103], off offset:256
	v_cvt_pk_bf16_f32 v164, v84, v85
	v_cvt_pk_bf16_f32 v165, v86, v87
	v_cvt_pk_bf16_f32 v166, v80, v81
	v_cvt_pk_bf16_f32 v167, v82, v83
	ds_bpermute_b32 v84, v220, v164
	ds_bpermute_b32 v85, v220, v165
	ds_bpermute_b32 v86, v220, v166
	ds_bpermute_b32 v87, v220, v167
	s_waitcnt lgkmcnt(4)
	global_store_dwordx4 v[228:229], v[92:95], off
	v_add_u32_e32 v238, 48, v217
	v_mul_lo_u32 v238, v238, s40
	v_lshl_add_u64 v[230:231], v[238:239], 1, v[236:237]
	v_cvt_pk_bf16_f32 v168, v76, v77
	v_cvt_pk_bf16_f32 v169, v78, v79
	v_cvt_pk_bf16_f32 v170, v72, v73
	v_cvt_pk_bf16_f32 v171, v74, v75
	ds_bpermute_b32 v76, v220, v168
	ds_bpermute_b32 v77, v220, v169
	ds_bpermute_b32 v78, v220, v170
	ds_bpermute_b32 v79, v220, v171
	s_waitcnt lgkmcnt(4)
	global_store_dwordx4 v[228:229], v[84:87], off offset:256
	v_cvt_pk_bf16_f32 v172, v68, v69
	v_cvt_pk_bf16_f32 v173, v70, v71
	v_cvt_pk_bf16_f32 v174, v64, v65
	v_cvt_pk_bf16_f32 v175, v66, v67
	ds_bpermute_b32 v68, v220, v172
	ds_bpermute_b32 v69, v220, v173
	ds_bpermute_b32 v70, v220, v174
	ds_bpermute_b32 v71, v220, v175
	s_waitcnt lgkmcnt(4)
	global_store_dwordx4 v[230:231], v[76:79], off
	v_add_u32_e32 v238, 0x80, v217
	v_mul_lo_u32 v238, v238, s40
	v_lshl_add_u64 v[224:225], v[238:239], 1, v[236:237]
	v_cvt_pk_bf16_f32 v160, v60, v61
	v_cvt_pk_bf16_f32 v161, v62, v63
	v_cvt_pk_bf16_f32 v162, v56, v57
	v_cvt_pk_bf16_f32 v163, v58, v59
	ds_bpermute_b32 v60, v220, v160
	ds_bpermute_b32 v61, v220, v161
	ds_bpermute_b32 v62, v220, v162
	ds_bpermute_b32 v63, v220, v163
	s_waitcnt lgkmcnt(4)
	global_store_dwordx4 v[230:231], v[68:71], off offset:256
	v_cvt_pk_bf16_f32 v164, v52, v53
	v_cvt_pk_bf16_f32 v165, v54, v55
	v_cvt_pk_bf16_f32 v166, v48, v49
	v_cvt_pk_bf16_f32 v167, v50, v51
	ds_bpermute_b32 v52, v220, v164
	ds_bpermute_b32 v53, v220, v165
	ds_bpermute_b32 v54, v220, v166
	ds_bpermute_b32 v55, v220, v167
	s_waitcnt lgkmcnt(4)
	global_store_dwordx4 v[224:225], v[60:63], off
	v_add_u32_e32 v238, 0x90, v217
	v_mul_lo_u32 v238, v238, s40
	v_lshl_add_u64 v[226:227], v[238:239], 1, v[236:237]
	v_cvt_pk_bf16_f32 v168, v44, v45
	v_cvt_pk_bf16_f32 v169, v46, v47
	v_cvt_pk_bf16_f32 v170, v40, v41
	v_cvt_pk_bf16_f32 v171, v42, v43
	ds_bpermute_b32 v44, v220, v168
	ds_bpermute_b32 v45, v220, v169
	ds_bpermute_b32 v46, v220, v170
	ds_bpermute_b32 v47, v220, v171
	s_waitcnt lgkmcnt(4)
	global_store_dwordx4 v[224:225], v[52:55], off offset:256
	v_cvt_pk_bf16_f32 v172, v36, v37
	v_cvt_pk_bf16_f32 v173, v38, v39
	v_cvt_pk_bf16_f32 v174, v32, v33
	v_cvt_pk_bf16_f32 v175, v34, v35
	ds_bpermute_b32 v36, v220, v172
	ds_bpermute_b32 v37, v220, v173
	ds_bpermute_b32 v38, v220, v174
	ds_bpermute_b32 v39, v220, v175
	s_waitcnt lgkmcnt(4)
	global_store_dwordx4 v[226:227], v[44:47], off
	v_add_u32_e32 v238, 0xa0, v217
	v_mul_lo_u32 v238, v238, s40
	v_lshl_add_u64 v[228:229], v[238:239], 1, v[236:237]
	v_cvt_pk_bf16_f32 v160, v28, v29
	v_cvt_pk_bf16_f32 v161, v30, v31
	v_cvt_pk_bf16_f32 v162, v24, v25
	v_cvt_pk_bf16_f32 v163, v26, v27
	ds_bpermute_b32 v28, v220, v160
	ds_bpermute_b32 v29, v220, v161
	ds_bpermute_b32 v30, v220, v162
	ds_bpermute_b32 v31, v220, v163
	s_waitcnt lgkmcnt(4)
	global_store_dwordx4 v[226:227], v[36:39], off offset:256
	v_cvt_pk_bf16_f32 v164, v20, v21
	v_cvt_pk_bf16_f32 v165, v22, v23
	v_cvt_pk_bf16_f32 v166, v16, v17
	v_cvt_pk_bf16_f32 v167, v18, v19
	ds_bpermute_b32 v20, v220, v164
	ds_bpermute_b32 v21, v220, v165
	ds_bpermute_b32 v22, v220, v166
	ds_bpermute_b32 v23, v220, v167
	s_waitcnt lgkmcnt(4)
	global_store_dwordx4 v[228:229], v[28:31], off
	v_add_u32_e32 v238, 0xb0, v217
	v_mul_lo_u32 v238, v238, s40
	v_lshl_add_u64 v[230:231], v[238:239], 1, v[236:237]
	v_cvt_pk_bf16_f32 v168, v12, v13
	v_cvt_pk_bf16_f32 v169, v14, v15
	v_cvt_pk_bf16_f32 v170, v8, v9
	v_cvt_pk_bf16_f32 v171, v10, v11
	ds_bpermute_b32 v12, v220, v168
	ds_bpermute_b32 v13, v220, v169
	ds_bpermute_b32 v14, v220, v170
	ds_bpermute_b32 v15, v220, v171
	s_waitcnt lgkmcnt(4)
	global_store_dwordx4 v[228:229], v[20:23], off offset:256
	v_cvt_pk_bf16_f32 v172, v4, v5
	v_cvt_pk_bf16_f32 v173, v6, v7
	v_cvt_pk_bf16_f32 v174, v0, v1
	v_cvt_pk_bf16_f32 v175, v2, v3
	ds_bpermute_b32 v4, v220, v172
	ds_bpermute_b32 v5, v220, v173
	ds_bpermute_b32 v6, v220, v174
	ds_bpermute_b32 v7, v220, v175
	s_waitcnt lgkmcnt(4)
	global_store_dwordx4 v[230:231], v[12:15], off
	s_waitcnt lgkmcnt(0)
	global_store_dwordx4 v[230:231], v[4:7], off offset:256
	s_and_saveexec_b64 s[38:39], s[6:7]
	global_store_dword v200, v176, s[36:37]
	v_add_u32_e32 v201, 0x800, v200
	global_store_dword v201, v177, s[36:37]
	v_add_u32_e32 v201, 0x1000, v200
	global_store_dword v201, v178, s[36:37]
	v_add_u32_e32 v201, 0x1800, v200
	global_store_dword v201, v179, s[36:37]
	v_add_u32_e32 v201, 0x4000, v200
	global_store_dword v201, v180, s[36:37]
	v_add_u32_e32 v201, 0x4800, v200
	global_store_dword v201, v181, s[36:37]
	v_add_u32_e32 v201, 0x5000, v200
	global_store_dword v201, v182, s[36:37]
	v_add_u32_e32 v201, 0x5800, v200
	global_store_dword v201, v183, s[36:37]
	s_branch .LBB0_517
